# HGRN chunk loop: wave-uniform exec-mask branch chain for the cross-part prefix offset replaced by three v_cmp/v_cndmask (no branches)
# baseline (speedup 1.0000x reference)
; __device__ __forceinline__ bf16_t f2bf(float f) { return (bf16_t)(cvt_pk_bf16(f, 0.f) & 0xffffu); }
; __device__ __forceinline__ float bf2f(bf16_t b) { return __uint_as_float(((unsigned)b) << 16); }
; __device__ __forceinline__ void hgrn_item(LAS unsigned char* lds, int item, const bf16_t* QS, const float* LF, const bf16_t* KK, const bf16_t* VV, bf16_t* YAB) {
;     ...
;         float bl[16]; float run = 0.f;
; #pragma unroll
;         for (int i = 0; i < 16; ++i) { run += lfv[i]; bl[i] = run; }
;         PS[part * 128 + k] = run;
;         __syncthreads();
;         const float p0 = PS[k], p1 = PS[128 + k], p2 = PS[256 + k], p3 = PS[384 + k];
;         const float pre = part == 0 ? 0.f : part == 1 ? p0 : part == 2 ? p0 + p1 : p0 + p1 + p2;
;         const float mref = p0 + p1, blast = (p0 + p1) + (p2 + p3);
;         const float em = __expf(mref), ebm = __expf(blast - mref);
;         float kd[16];
; #pragma unroll
;         for (int i = 0; i < 16; ++i) {
;             const float bb = pre + bl[i];
;             const float e1 = __expf(fminf(fmaxf(bb - mref, -80.f), 80.f)), e2 = __builtin_amdgcn_rcpf(e1);
;             const float q = bf2f(qv[i]), kx = bf2f(kv[i]);
;             const int s = part * 16 + i;
;             QT[s * 136 + k] = f2bf(q * e1); KT[s * 136 + k] = f2bf(kx * e2); QH[s * 136 + k] = f2bf(q * e1 * em); kd[i] = kx * e2 * ebm;
.LBB0_693:
	v_add_f32_e32 v224, 0, v171
	v_add_f32_e32 v223, v175, v224
	v_add_f32_e32 v25, v181, v223
	v_add_f32_e32 v24, v183, v25
	v_add_f32_e32 v222, v24, v185
	v_add_f32_e32 v221, v222, v187
	v_add_f32_e32 v220, v221, v169
	v_add_f32_e32 v219, v220, v173
	v_add_f32_e32 v218, v219, v188
	v_add_f32_e32 v217, v218, v190
	v_add_f32_e32 v216, v217, v192
	v_add_f32_e32 v215, v216, v195
	v_add_f32_e32 v214, v215, v198
	v_add_f32_e32 v212, v214, v201
	v_add_f32_e32 v210, v212, v197
	v_add_f32_e32 v26, v210, v202
	ds_write_b32 v125, v26
	s_waitcnt lgkmcnt(0)
	s_barrier
	ds_read2st64_b32 v[20:21], v126 offset1:2
	ds_read2st64_b32 v[22:23], v126 offset0:4 offset1:6
	s_waitcnt lgkmcnt(0)
	v_add_f32_e32 v226, v20, v21
	v_cmp_eq_u32_e32 vcc, 1, v167
	v_cmp_eq_u32_e64 s[58:59], 2, v167
	v_cmp_eq_u32_e64 s[60:61], 3, v167
	v_add_f32_e32 v227, v226, v22
	v_cndmask_b32_e32 v211, 0, v20, vcc
	v_cndmask_b32_e64 v211, v211, v226, s[58:59]
	v_cndmask_b32_e64 v211, v211, v227, s[60:61]
	s_waitcnt lgkmcnt(0)
	v_mov_b32_e32 v226, v23
	v_mov_b32_e32 v227, v20
	v_mov_b32_e32 v23, v21
	s_add_u32 s98, s24, 0x35e40000
	s_addc_u32 s99, s25, 0
	global_load_dword v171, v102, s[98:99]
	v_pk_add_f32 v[20:21], v[226:227], v[22:23]
	v_add_f32_e32 v223, v223, v211
	v_mul_f32_e32 v22, 0x3fb8aa3b, v21
	v_exp_f32_e32 v213, v22
	s_add_u32 s98, s24, 0x35e41000
	s_addc_u32 s99, s25, 0
	global_load_dword v175, v102, s[98:99]
	v_add_f32_e32 v22, v224, v211
	v_sub_f32_e32 v22, v22, v21
	v_med3_f32 v22, v22, s2, v165
	v_mul_f32_e32 v22, 0x3fb8aa3b, v22
	s_add_u32 s98, s24, 0x35e42000
	s_addc_u32 s99, s25, 0
	global_load_dword v181, v102, s[98:99]
	v_exp_f32_e32 v23, v22
	v_sub_f32_e32 v223, v223, v21
	v_med3_f32 v223, v223, s2, v165
	v_mul_f32_e32 v223, 0x3fb8aa3b, v223
	s_add_u32 s98, s24, 0x35e43000
	s_addc_u32 s99, s25, 0
	global_load_dword v183, v102, s[98:99]
	v_lshlrev_b32_e32 v224, 16, v172
	v_exp_f32_e32 v223, v223
	v_rcp_f32_e32 v22, v23
	v_mul_f32_e32 v23, v23, v224
	s_add_u32 s98, s24, 0x35e44000
	s_addc_u32 s99, s25, 0
	global_load_dword v185, v102, s[98:99]
	v_cvt_pk_bf16_f32 v224, v23, s0
	v_mul_f32_e32 v23, v213, v23
	v_add_f32_e32 v20, v21, v20
	v_cvt_pk_bf16_f32 v23, v23, s0
	s_add_u32 s98, s24, 0x35e45000
	s_addc_u32 s99, s25, 0
	global_load_dword v187, v102, s[98:99]
	v_sub_f32_e32 v20, v20, v21
	ds_write_b16 v135, v23 offset:34816
	v_rcp_f32_e32 v23, v223
	v_add_f32_e32 v25, v25, v211
	s_add_u32 s98, s24, 0x35e46000
	s_addc_u32 s99, s25, 0
	global_load_dword v169, v102, s[98:99]
	v_mul_f32_e32 v20, 0x3fb8aa3b, v20
	v_sub_f32_e32 v25, v25, v21
	v_exp_f32_e32 v20, v20
	ds_write_b16 v135, v224
	s_add_u32 s98, s24, 0x35e47000
	s_addc_u32 s99, s25, 0
	global_load_dword v173, v102, s[98:99]
	v_lshlrev_b32_e32 v224, 16, v180
	v_med3_f32 v25, v25, s2, v165
	v_mul_f32_e32 v223, v223, v224
	v_and_b32_e32 v225, 0xffff0000, v81
	s_add_u32 s98, s24, 0x35e48000
	s_addc_u32 s99, s25, 0
	global_load_dword v188, v102, s[98:99]
	v_lshlrev_b32_e32 v224, 16, v81
	v_mul_f32_e32 v25, 0x3fb8aa3b, v25
	v_add_f32_e32 v24, v24, v211
	v_pk_mul_f32 v[224:225], v[22:23], v[224:225]
	s_add_u32 s98, s24, 0x35e49000
	s_addc_u32 s99, s25, 0
	global_load_dword v190, v102, s[98:99]
	v_exp_f32_e32 v25, v25
	v_sub_f32_e32 v24, v24, v21
	v_cvt_pk_bf16_f32 v226, v223, s0
	v_mul_f32_e32 v223, v213, v223
	s_add_u32 s98, s24, 0x35e4a000
	s_addc_u32 s99, s25, 0
	global_load_dword v192, v102, s[98:99]
	v_cvt_pk_bf16_f32 v22, v224, s0
	v_med3_f32 v24, v24, s2, v165
	v_cvt_pk_bf16_f32 v223, v223, s0
	ds_write_b16 v135, v22 offset:17408
	s_add_u32 s98, s24, 0x35e4b000
	s_addc_u32 s99, s25, 0
	global_load_dword v195, v102, s[98:99]
	v_pk_mul_f32 v[22:23], v[20:21], v[224:225] op_sel_hi:[0,1]
	v_cvt_pk_bf16_f32 v224, v225, s0
	v_mul_f32_e32 v24, 0x3fb8aa3b, v24
	ds_write_b16 v136, v226
	s_add_u32 s98, s24, 0x35e4c000
	s_addc_u32 s99, s25, 0
	global_load_dword v198, v102, s[98:99]
	ds_write_b16 v136, v224 offset:17408
	ds_write_b16 v136, v223 offset:34816
	v_lshlrev_b32_e32 v223, 16, v182
	v_exp_f32_e32 v24, v24
	s_add_u32 s98, s24, 0x35e4d000
	s_addc_u32 s99, s25, 0
	global_load_dword v201, v102, s[98:99]
	v_rcp_f32_e32 v224, v25
	v_mul_f32_e32 v25, v25, v223
	v_cvt_pk_bf16_f32 v223, v25, s0
	v_mul_f32_e32 v25, v213, v25
	s_add_u32 s98, s24, 0x35e4e000
	s_addc_u32 s99, s25, 0
	global_load_dword v197, v102, s[98:99]
	v_add_u32_e32 v226, v43, v55
	v_cvt_pk_bf16_f32 v25, v25, s0
	v_add_f32_e32 v222, v222, v211
	ds_write_b16 v226, v25 offset:35088
	s_add_u32 s98, s24, 0x35e4f000
	s_addc_u32 s99, s25, 0
	global_load_dword v202, v102, s[98:99]
	v_rcp_f32_e32 v225, v24
	v_lshlrev_b32_e32 v25, 16, v184
	v_sub_f32_e32 v222, v222, v21
	v_mul_f32_e32 v24, v24, v25
	s_add_u32 s98, s24, 0x1de20000
	s_addc_u32 s99, s25, 0
	global_load_ushort v172, v100, s[98:99]
	v_med3_f32 v222, v222, s2, v165
	ds_write_b16 v226, v223 offset:272
	v_cvt_pk_bf16_f32 v223, v24, s0
	v_mul_f32_e32 v24, v213, v24
	s_add_u32 s98, s24, 0x1de20000
	s_addc_u32 s99, s25, 0
	global_load_ushort v180, v100, s[98:99] offset:2048
	v_mul_f32_e32 v222, 0x3fb8aa3b, v222
	v_add_f32_e32 v221, v221, v211
	v_cvt_pk_bf16_f32 v227, v24, s0
	v_and_b32_e32 v25, 0xffff0000, v91
	s_add_u32 s98, s24, 0x21e20000
	s_addc_u32 s99, s25, 0
	global_load_ushort v81, v100, s[98:99]
	global_load_ushort v232, v100, s[98:99] offset:2048
	v_lshlrev_b32_e32 v24, 16, v91
	ds_write_b16 v226, v223 offset:544
	v_exp_f32_e32 v223, v222
	v_sub_f32_e32 v221, v221, v21
	s_add_u32 s98, s24, 0x1de21000
	s_addc_u32 s99, s25, 0
	global_load_ushort v182, v100, s[98:99]
	v_pk_mul_f32 v[224:225], v[224:225], v[24:25]
	v_med3_f32 v221, v221, s2, v165
	v_cvt_pk_bf16_f32 v24, v224, s0
; __device__ __forceinline__ bf16_t f2bf(float f) { return (bf16_t)(cvt_pk_bf16(f, 0.f) & 0xffffu); }
; __device__ __forceinline__ float bf2f(bf16_t b) { return __uint_as_float(((unsigned)b) << 16); }
; __device__ __forceinline__ void hgrn_item(LAS unsigned char* lds, int item, const bf16_t* QS, const float* LF, const bf16_t* KK, const bf16_t* VV, bf16_t* YAB) {
;     ...
;         for (int i = 0; i < 16; ++i) {
;             const float bb = pre + bl[i];
;             const float e1 = __expf(fminf(fmaxf(bb - mref, -80.f), 80.f)), e2 = __builtin_amdgcn_rcpf(e1);
;             const float q = bf2f(qv[i]), kx = bf2f(kv[i]);
;             const int s = part * 16 + i;
;             QT[s * 136 + k] = f2bf(q * e1); KT[s * 136 + k] = f2bf(kx * e2); QH[s * 136 + k] = f2bf(q * e1 * em); kd[i] = kx * e2 * ebm;
	v_mul_f32_e32 v221, 0x3fb8aa3b, v221
	s_add_u32 s98, s24, 0x1de21000
	s_addc_u32 s99, s25, 0
	global_load_ushort v184, v100, s[98:99] offset:2048
	ds_write_b16 v226, v24 offset:17680
	v_pk_mul_f32 v[24:25], v[20:21], v[224:225] op_sel_hi:[0,1]
	v_cvt_pk_bf16_f32 v222, v225, s0
	v_lshlrev_b32_e32 v224, 16, v186
	s_add_u32 s98, s24, 0x21e21000
	s_addc_u32 s99, s25, 0
	global_load_ushort v91, v100, s[98:99]
	global_load_ushort v233, v100, s[98:99] offset:2048
	v_exp_f32_e32 v221, v221
	ds_write_b16 v226, v222 offset:17952
	ds_write_b16 v226, v227 offset:35360
	v_rcp_f32_e32 v222, v223
	s_add_u32 s98, s24, 0x1de22000
	s_addc_u32 s99, s25, 0
	global_load_ushort v186, v100, s[98:99]
	v_mul_f32_e32 v223, v223, v224
	v_cvt_pk_bf16_f32 v224, v223, s0
	v_mul_f32_e32 v223, v213, v223
	v_cvt_pk_bf16_f32 v223, v223, s0
	ds_write_b16 v226, v223 offset:35632
	v_rcp_f32_e32 v223, v221
	ds_write_b16 v226, v224 offset:816
	v_lshlrev_b32_e32 v224, 16, v168
	s_add_u32 s98, s24, 0x1de22000
	s_addc_u32 s99, s25, 0
	global_load_ushort v168, v100, s[98:99] offset:2048
	v_add_f32_e32 v220, v220, v211
	v_mul_f32_e32 v221, v221, v224
	v_and_b32_e32 v225, 0xffff0000, v204
	v_lshlrev_b32_e32 v224, 16, v204
	s_add_u32 s98, s24, 0x21e22000
	s_addc_u32 s99, s25, 0
	global_load_ushort v204, v100, s[98:99]
	global_load_ushort v234, v100, s[98:99] offset:2048
	v_sub_f32_e32 v220, v220, v21
	v_pk_mul_f32 v[222:223], v[222:223], v[224:225]
	v_med3_f32 v220, v220, s2, v165
	v_cvt_pk_bf16_f32 v224, v222, s0
	v_mul_f32_e32 v220, 0x3fb8aa3b, v220
	v_add_f32_e32 v219, v219, v211
	ds_write_b16 v226, v224 offset:18224
	v_pk_mul_f32 v[224:225], v[20:21], v[222:223] op_sel_hi:[0,1]
	v_exp_f32_e32 v222, v220
	v_sub_f32_e32 v219, v219, v21
	v_cvt_pk_bf16_f32 v227, v221, s0
	v_mul_f32_e32 v221, v213, v221
	v_med3_f32 v219, v219, s2, v165
	v_cvt_pk_bf16_f32 v221, v221, s0
	v_cvt_pk_bf16_f32 v220, v223, s0
	v_mul_f32_e32 v219, 0x3fb8aa3b, v219
	ds_write_b16 v226, v227 offset:1088
	ds_write_b16 v226, v220 offset:18496
	ds_write_b16 v226, v221 offset:35904
	v_lshlrev_b32_e32 v221, 16, v170
	s_add_u32 s98, s24, 0x1de23000
	s_addc_u32 s99, s25, 0
	global_load_ushort v170, v100, s[98:99]
	v_exp_f32_e32 v219, v219
	v_mul_f32_e32 v221, v222, v221
	v_rcp_f32_e32 v220, v222
	v_cvt_pk_bf16_f32 v222, v221, s0
	v_mul_f32_e32 v221, v213, v221
	v_cvt_pk_bf16_f32 v221, v221, s0
	ds_write_b16 v226, v221 offset:36176
	v_rcp_f32_e32 v221, v219
	ds_write_b16 v226, v222 offset:1360
	v_lshlrev_b32_e32 v222, 16, v174
	s_add_u32 s98, s24, 0x1de23000
	s_addc_u32 s99, s25, 0
	global_load_ushort v174, v100, s[98:99] offset:2048
	v_add_f32_e32 v218, v218, v211
	v_mul_f32_e32 v219, v219, v222
	v_and_b32_e32 v223, 0xffff0000, v205
	v_lshlrev_b32_e32 v222, 16, v205
	s_add_u32 s98, s24, 0x21e23000
	s_addc_u32 s99, s25, 0
	global_load_ushort v205, v100, s[98:99]
	global_load_ushort v235, v100, s[98:99] offset:2048
	v_sub_f32_e32 v218, v218, v21
	v_pk_mul_f32 v[220:221], v[220:221], v[222:223]
	v_med3_f32 v218, v218, s2, v165
	v_cvt_pk_bf16_f32 v222, v220, s0
	v_mul_f32_e32 v218, 0x3fb8aa3b, v218
	v_add_f32_e32 v217, v217, v211
	ds_write_b16 v226, v222 offset:18768
	v_pk_mul_f32 v[222:223], v[20:21], v[220:221] op_sel_hi:[0,1]
	v_exp_f32_e32 v220, v218
	v_sub_f32_e32 v217, v217, v21
	v_cvt_pk_bf16_f32 v227, v219, s0
	v_mul_f32_e32 v219, v213, v219
	v_med3_f32 v217, v217, s2, v165
	v_cvt_pk_bf16_f32 v219, v219, s0
	v_cvt_pk_bf16_f32 v218, v221, s0
	v_mul_f32_e32 v217, 0x3fb8aa3b, v217
	ds_write_b16 v226, v227 offset:1632
	ds_write_b16 v226, v218 offset:19040
	ds_write_b16 v226, v219 offset:36448
	v_lshlrev_b32_e32 v219, 16, v189
	s_add_u32 s98, s24, 0x1de24000
	s_addc_u32 s99, s25, 0
	global_load_ushort v189, v100, s[98:99]
	v_exp_f32_e32 v217, v217
	v_mul_f32_e32 v219, v220, v219
	v_rcp_f32_e32 v218, v220
	v_cvt_pk_bf16_f32 v220, v219, s0
	v_mul_f32_e32 v219, v213, v219
	v_cvt_pk_bf16_f32 v219, v219, s0
	ds_write_b16 v226, v219 offset:36720
	v_rcp_f32_e32 v219, v217
	ds_write_b16 v226, v220 offset:1904
	v_lshlrev_b32_e32 v220, 16, v191
	s_add_u32 s98, s24, 0x1de24000
	s_addc_u32 s99, s25, 0
	global_load_ushort v191, v100, s[98:99] offset:2048
	v_add_f32_e32 v216, v216, v211
	v_mul_f32_e32 v217, v217, v220
	v_and_b32_e32 v221, 0xffff0000, v206
	v_lshlrev_b32_e32 v220, 16, v206
	s_add_u32 s98, s24, 0x21e24000
	s_addc_u32 s99, s25, 0
	global_load_ushort v206, v100, s[98:99]
	global_load_ushort v236, v100, s[98:99] offset:2048
	v_sub_f32_e32 v216, v216, v21
	v_pk_mul_f32 v[218:219], v[218:219], v[220:221]
	v_med3_f32 v216, v216, s2, v165
	v_cvt_pk_bf16_f32 v220, v218, s0
	v_mul_f32_e32 v216, 0x3fb8aa3b, v216
	v_add_f32_e32 v215, v215, v211
	ds_write_b16 v226, v220 offset:19312
	v_pk_mul_f32 v[220:221], v[20:21], v[218:219] op_sel_hi:[0,1]
	v_exp_f32_e32 v218, v216
	v_sub_f32_e32 v215, v215, v21
	v_cvt_pk_bf16_f32 v227, v217, s0
	v_mul_f32_e32 v217, v213, v217
	v_med3_f32 v215, v215, s2, v165
	v_cvt_pk_bf16_f32 v217, v217, s0
	v_cvt_pk_bf16_f32 v216, v219, s0
	v_mul_f32_e32 v215, 0x3fb8aa3b, v215
	ds_write_b16 v226, v227 offset:2176
	ds_write_b16 v226, v216 offset:19584
	ds_write_b16 v226, v217 offset:36992
	v_lshlrev_b32_e32 v217, 16, v193
	s_add_u32 s98, s24, 0x1de25000
	s_addc_u32 s99, s25, 0
	global_load_ushort v193, v100, s[98:99]
	v_exp_f32_e32 v215, v215
	v_mul_f32_e32 v217, v218, v217
	v_rcp_f32_e32 v216, v218
	v_cvt_pk_bf16_f32 v218, v217, s0
; #define LAS __attribute__((address_space(3)))
; __device__ __forceinline__ unsigned cvt_pk_bf16(float lo, float hi) { f32x2_c v = {lo, hi}; bf16x2_c r = __builtin_convertvector(v, bf16x2_c); return __builtin_bit_cast(unsigned, r); }
; __device__ __forceinline__ bf16_t f2bf(float f) { return (bf16_t)(cvt_pk_bf16(f, 0.f) & 0xffffu); }
; __device__ __forceinline__ float bf2f(bf16_t b) { return __uint_as_float(((unsigned)b) << 16); }
; #define HG_LOAD(c) do { const size_t r_ = row0 + (size_t)(c) * 64; \
;         _Pragma("unroll") for (int i = 0; i < 16; ++i) { const size_t p_ = (r_ + part * 16 + i) * HW + colq; lfv[i] = LF[p_]; qv[i] = QS[p_]; kv[i] = KK[p_]; } \
;         _Pragma("unroll") for (int i = 0; i < 8; ++i) vr[i] = VV[(r_ + sg * 8 + i) * HW + colv]; } while (0)
; __device__ __forceinline__ void hgrn_item(LAS unsigned char* lds, int item, const bf16_t* QS, const float* LF, const bf16_t* KK, const bf16_t* VV, bf16_t* YAB) {
;     ...
; #pragma unroll
;         for (int i = 0; i < 16; ++i) {
;             const float bb = pre + bl[i];
;             const float e1 = __expf(fminf(fmaxf(bb - mref, -80.f), 80.f)), e2 = __builtin_amdgcn_rcpf(e1);
;             const float q = bf2f(qv[i]), kx = bf2f(kv[i]);
;             const int s = part * 16 + i;
;             QT[s * 136 + k] = f2bf(q * e1); KT[s * 136 + k] = f2bf(kx * e2); QH[s * 136 + k] = f2bf(q * e1 * em); kd[i] = kx * e2 * ebm;
;         }
;         { u32x4 w0, w1;
;           w0.x = cvt_pk_bf16(kd[0], kd[1]); w0.y = cvt_pk_bf16(kd[2], kd[3]); w0.z = cvt_pk_bf16(kd[4], kd[5]); w0.w = cvt_pk_bf16(kd[6], kd[7]);
;           w1.x = cvt_pk_bf16(kd[8], kd[9]); w1.y = cvt_pk_bf16(kd[10], kd[11]); w1.z = cvt_pk_bf16(kd[12], kd[13]); w1.w = cvt_pk_bf16(kd[14], kd[15]);
;           *(LAS u32x4*)(KD + k * 72 + part * 16) = w0; *(LAS u32x4*)(KD + k * 72 + part * 16 + 8) = w1; }
;         if (part == 0) DD[k] = em * ebm;
;         { u32x4 w; w.x = (unsigned)vr[0] | ((unsigned)vr[1] << 16); w.y = (unsigned)vr[2] | ((unsigned)vr[3] << 16); w.z = (unsigned)vr[4] | ((unsigned)vr[5] << 16); w.w = (unsigned)vr[6] | ((unsigned)vr[7] << 16);
;           *(LAS u32x4*)(VT + vv * 72 + sg * 8) = w; }
;         __syncthreads();
;         if (c + 1 < 64) HG_LOAD(c + 1);
	v_mul_f32_e32 v217, v213, v217
	v_cvt_pk_bf16_f32 v217, v217, s0
	ds_write_b16 v226, v217 offset:37264
	v_rcp_f32_e32 v217, v215
	ds_write_b16 v226, v218 offset:2448
	v_lshlrev_b32_e32 v218, 16, v196
	s_add_u32 s98, s24, 0x1de25000
	s_addc_u32 s99, s25, 0
	global_load_ushort v196, v100, s[98:99] offset:2048
	v_add_f32_e32 v214, v214, v211
	v_mul_f32_e32 v215, v215, v218
	v_and_b32_e32 v219, 0xffff0000, v207
	v_lshlrev_b32_e32 v218, 16, v207
	s_add_u32 s98, s24, 0x21e25000
	s_addc_u32 s99, s25, 0
	global_load_ushort v207, v100, s[98:99]
	global_load_ushort v237, v100, s[98:99] offset:2048
	v_sub_f32_e32 v214, v214, v21
	v_pk_mul_f32 v[216:217], v[216:217], v[218:219]
	v_med3_f32 v214, v214, s2, v165
	v_cvt_pk_bf16_f32 v218, v216, s0
	v_mul_f32_e32 v214, 0x3fb8aa3b, v214
	v_add_f32_e32 v212, v212, v211
	ds_write_b16 v226, v218 offset:19856
	v_pk_mul_f32 v[218:219], v[20:21], v[216:217] op_sel_hi:[0,1]
	v_exp_f32_e32 v216, v214
	v_sub_f32_e32 v212, v212, v21
	v_cvt_pk_bf16_f32 v227, v215, s0
	v_mul_f32_e32 v215, v213, v215
	v_med3_f32 v212, v212, s2, v165
	v_cvt_pk_bf16_f32 v215, v215, s0
	v_cvt_pk_bf16_f32 v214, v217, s0
	v_mul_f32_e32 v212, 0x3fb8aa3b, v212
	ds_write_b16 v226, v227 offset:2720
	ds_write_b16 v226, v214 offset:20128
	ds_write_b16 v226, v215 offset:37536
	v_lshlrev_b32_e32 v215, 16, v200
	s_add_u32 s98, s24, 0x1de26000
	s_addc_u32 s99, s25, 0
	global_load_ushort v200, v100, s[98:99]
	v_exp_f32_e32 v212, v212
	v_mul_f32_e32 v215, v216, v215
	v_rcp_f32_e32 v214, v216
	v_cvt_pk_bf16_f32 v216, v215, s0
	v_mul_f32_e32 v215, v213, v215
	v_cvt_pk_bf16_f32 v215, v215, s0
	ds_write_b16 v226, v215 offset:37808
	v_rcp_f32_e32 v215, v212
	ds_write_b16 v226, v216 offset:2992
	v_lshlrev_b32_e32 v216, 16, v194
	s_add_u32 s98, s24, 0x1de26000
	s_addc_u32 s99, s25, 0
	global_load_ushort v194, v100, s[98:99] offset:2048
	v_mul_f32_e32 v212, v212, v216
	v_and_b32_e32 v217, 0xffff0000, v208
	v_lshlrev_b32_e32 v216, 16, v208
	v_pk_mul_f32 v[214:215], v[214:215], v[216:217]
	s_add_u32 s98, s24, 0x21e26000
	s_addc_u32 s99, s25, 0
	global_load_ushort v208, v100, s[98:99]
	global_load_ushort v238, v100, s[98:99] offset:2048
	v_add_f32_e32 v210, v210, v211
	v_cvt_pk_bf16_f32 v216, v214, s0
	v_sub_f32_e32 v210, v210, v21
	v_add_f32_e32 v26, v26, v211
	ds_write_b16 v226, v216 offset:20400
	v_pk_mul_f32 v[216:217], v[20:21], v[214:215] op_sel_hi:[0,1]
	v_med3_f32 v210, v210, s2, v165
	v_sub_f32_e32 v21, v26, v21
	v_mul_f32_e32 v210, 0x3fb8aa3b, v210
	v_med3_f32 v21, v21, s2, v165
	v_exp_f32_e32 v214, v210
	v_mul_f32_e32 v21, 0x3fb8aa3b, v21
	v_cvt_pk_bf16_f32 v227, v212, s0
	v_mul_f32_e32 v212, v213, v212
	v_exp_f32_e32 v21, v21
	v_cvt_pk_bf16_f32 v212, v212, s0
	v_cvt_pk_bf16_f32 v210, v215, s0
	ds_write_b16 v226, v227 offset:3264
	ds_write_b16 v226, v210 offset:20672
	ds_write_b16 v226, v212 offset:38080
	v_lshlrev_b32_e32 v212, 16, v199
	s_add_u32 s98, s24, 0x1de27000
	s_addc_u32 s99, s25, 0
	global_load_ushort v199, v100, s[98:99]
	v_mul_f32_e32 v212, v214, v212
	v_rcp_f32_e32 v210, v214
	v_mul_f32_e32 v26, v213, v212
	v_rcp_f32_e32 v211, v21
	v_cvt_pk_bf16_f32 v26, v26, s0
	v_cvt_pk_bf16_f32 v214, v212, s0
	ds_write_b16 v226, v26 offset:38352
	v_lshlrev_b32_e32 v26, 16, v203
	s_add_u32 s98, s24, 0x1de27000
	s_addc_u32 s99, s25, 0
	global_load_ushort v203, v100, s[98:99] offset:2048
	ds_write_b16 v226, v214 offset:3536
	v_mul_f32_e32 v21, v21, v26
	v_and_b32_e32 v215, 0xffff0000, v209
	v_lshlrev_b32_e32 v214, 16, v209
	s_add_u32 s98, s24, 0x21e27000
	s_addc_u32 s99, s25, 0
	global_load_ushort v209, v100, s[98:99]
	global_load_ushort v239, v100, s[98:99] offset:2048
	v_cvt_pk_bf16_f32 v26, v21, s0
	v_mul_f32_e32 v21, v213, v21
	v_pk_mul_f32 v[210:211], v[210:211], v[214:215]
	v_cvt_pk_bf16_f32 v21, v21, s0
	v_cvt_pk_bf16_f32 v212, v210, s0
	ds_write_b16 v226, v212 offset:20944
	ds_write_b16 v226, v26 offset:3808
	v_cvt_pk_bf16_f32 v26, v211, s0
	v_cvt_pk_bf16_f32 v22, v22, v23
	v_cvt_pk_bf16_f32 v23, v24, v25
	v_cvt_pk_bf16_f32 v24, v224, v225
	v_cvt_pk_bf16_f32 v25, v222, v223
	v_pk_mul_f32 v[210:211], v[20:21], v[210:211] op_sel_hi:[0,1]
	ds_write_b16 v226, v26 offset:21216
	ds_write_b16 v226, v21 offset:38624
	v_cvt_pk_bf16_f32 v214, v220, v221
	v_cvt_pk_bf16_f32 v215, v218, v219
	v_cvt_pk_bf16_f32 v216, v216, v217
	v_cvt_pk_bf16_f32 v217, v210, v211
	ds_write_b128 v127, v[22:25] offset:52224
	ds_write_b128 v127, v[214:217] offset:52240
	s_and_saveexec_b64 s[38:39], s[72:73]
	v_mul_f32_e32 v20, v213, v20
	ds_write_b32 v134, v20
	s_or_b64 exec, exec, s[38:39]
	s_cmp_eq_u32 s0, 0xfc0000
	ds_write_b128 v128, v[8:11]
	s_add_u32 s98, s24, 0x25e20000
	s_addc_u32 s99, s25, 0
	global_load_ushort v8, v98, s[98:99]
	global_load_ushort v240, v98, s[98:99] offset:2048
	s_add_u32 s98, s24, 0x25e21000
	s_addc_u32 s99, s25, 0
	global_load_ushort v9, v98, s[98:99]
	global_load_ushort v241, v98, s[98:99] offset:2048
	s_add_u32 s98, s24, 0x25e22000
	s_addc_u32 s99, s25, 0
	global_load_ushort v10, v98, s[98:99]
	global_load_ushort v242, v98, s[98:99] offset:2048
	s_add_u32 s98, s24, 0x25e23000
	s_addc_u32 s99, s25, 0
	global_load_ushort v11, v98, s[98:99]
	global_load_ushort v243, v98, s[98:99] offset:2048
	s_waitcnt lgkmcnt(0)
	s_barrier
	s_cbranch_scc1 .LBB0_705
	s_mov_b64 s[90:91], s[26:27]
	s_mov_b64 s[88:89], s[24:25]
	s_mov_b64 s[86:87], s[22:23]
	s_mov_b64 s[84:85], s[20:21]

; #define LAS __attribute__((address_space(3)))
; __device__ __forceinline__ bf16_t f2bf(float f) { return (bf16_t)(cvt_pk_bf16(f, 0.f) & 0xffffu); }
; #define MFMA16(a, b, c) __builtin_amdgcn_mfma_f32_16x16x32_bf16((a), (b), (c), 0, 0, 0)
; __device__ __forceinline__ void hgrn_item(LAS unsigned char* lds, int item, const bf16_t* QS, const float* LF, const bf16_t* KK, const bf16_t* VV, bf16_t* YAB) {
;     ...
;         const float p0 = PS[k], p1 = PS[128 + k], p2 = PS[256 + k], p3 = PS[384 + k];
;         const float pre = part == 0 ? 0.f : part == 1 ? p0 : part == 2 ? p0 + p1 : p0 + p1 + p2;
;     ...
;                 if (si <= ti) {
; #pragma unroll
;                     for (int ks = 0; ks < 4; ++ks) {
;                         const bf16x8 af = *(const LAS bf16x8*)(QT + (ti * 16 + l15) * 136 + ks * 32 + quad * 8);
;                         const bf16x8 bfr = *(const LAS bf16x8*)(KT + (si * 16 + l15) * 136 + ks * 32 + quad * 8);
;                         a = MFMA16(af, bfr, a);
;                     }
;                 }
; #pragma unroll
;                 for (int j = 0; j < 4; ++j) { const int t = ti * 16 + quad * 4 + j, s = si * 16 + l15; PP[t * 72 + s] = f2bf((s <= t) ? a[j] : 0.f); }
.LBB0_707:
	s_or_b64 exec, exec, s[38:39]
	s_nop 6
	v_cvt_pk_bf16_f32 v21, v22, s0
	v_cndmask_b32_e64 v21, v21, 0, s[64:65]
	ds_write_b16 v154, v21
	v_cvt_pk_bf16_f32 v21, v23, s0
	v_cndmask_b32_e64 v21, v21, 0, s[42:43]
	ds_write_b16 v154, v21 offset:144
	v_cvt_pk_bf16_f32 v21, v24, s0
	v_cndmask_b32_e64 v21, v21, 0, s[44:45]
	ds_write_b16 v154, v21 offset:288
	v_cvt_pk_bf16_f32 v21, v25, s0
	v_cndmask_b32_e64 v21, v21, 0, s[36:37]
	ds_write_b16 v154, v21 offset:432
	v_mov_b32_e32 v21, 0
	v_mov_b32_e32 v22, 0
	v_mov_b32_e32 v23, 0
	s_and_saveexec_b64 s[38:39], s[48:49]
	s_cbranch_execz .LBB0_692
	ds_read_b128 v[20:23], v129
	ds_read_b128 v[210:213], v26 offset:21760
	ds_read_b128 v[214:217], v129 offset:64
	ds_read_b128 v[218:221], v26 offset:21824
	ds_read_b128 v[222:225], v129 offset:128
	ds_read_b128 v[226:229], v26 offset:21888
	s_waitcnt lgkmcnt(4)
	v_mfma_f32_16x16x32_bf16 v[20:23], v[20:23], v[210:213], 0
	ds_read_b128 v[210:213], v129 offset:192
	s_waitcnt lgkmcnt(3)
	v_mfma_f32_16x16x32_bf16 v[20:23], v[214:217], v[218:221], v[20:23]
	ds_read_b128 v[214:217], v26 offset:21952
	s_waitcnt lgkmcnt(2)
	v_mfma_f32_16x16x32_bf16 v[20:23], v[222:225], v[226:229], v[20:23]
	s_waitcnt lgkmcnt(0)
	v_mfma_f32_16x16x32_bf16 v[20:23], v[210:213], v[214:217], v[20:23]
	s_branch .LBB0_692
.LBB0_711:
	v_readlane_b32 s80, v244, 16
	v_readlane_b32 s81, v244, 17
	v_readlane_b32 s82, v244, 36
